# differential attention: per-lane half row sums kept through the KV loop, the two halves added once per item (no per-tile ds_bpermute + lgkmcnt(0))
# speedup vs baseline: 1.0067x; 1.0032x over previous
; __device__ __forceinline__ void diff_attn_item(CParams& p, int j, int layer, LAS unsigned char* lds, int b, int h, int qb, int tid_in, int lane_in, int wave) {
;     ...
;         float ls = 0.f;
; #pragma unroll
;         for (int sub = 0; sub < 2; ++sub)
; #pragma unroll
;             for (int i = 0; i < 16; ++i) { const float e = __builtin_amdgcn_exp2f(sc[sub][i] - m_new); sc[sub][i] = e; ls += e; }
;         ls += __shfl_xor(ls, 32);
;         l_run = l_run * alpha + ls; m_run = m_new;
.LdiffA_t:
	s_waitcnt lgkmcnt(0)
	v_sub_f32_e32 v246, v201, v213
	v_pk_add_f32 v[162:163], v[162:163], v[246:247] op_sel_hi:[1,0] neg_lo:[0,1] neg_hi:[0,1]
	v_pk_add_f32 v[164:165], v[164:165], v[246:247] op_sel_hi:[1,0] neg_lo:[0,1] neg_hi:[0,1]
	v_pk_add_f32 v[166:167], v[166:167], v[246:247] op_sel_hi:[1,0] neg_lo:[0,1] neg_hi:[0,1]
	v_pk_add_f32 v[168:169], v[168:169], v[246:247] op_sel_hi:[1,0] neg_lo:[0,1] neg_hi:[0,1]
	v_pk_add_f32 v[170:171], v[170:171], v[246:247] op_sel_hi:[1,0] neg_lo:[0,1] neg_hi:[0,1]
	v_pk_add_f32 v[172:173], v[172:173], v[246:247] op_sel_hi:[1,0] neg_lo:[0,1] neg_hi:[0,1]
	v_pk_add_f32 v[174:175], v[174:175], v[246:247] op_sel_hi:[1,0] neg_lo:[0,1] neg_hi:[0,1]
	v_pk_add_f32 v[176:177], v[176:177], v[246:247] op_sel_hi:[1,0] neg_lo:[0,1] neg_hi:[0,1]
	v_pk_add_f32 v[228:229], v[228:229], v[246:247] op_sel_hi:[1,0] neg_lo:[0,1] neg_hi:[0,1]
	v_pk_add_f32 v[230:231], v[230:231], v[246:247] op_sel_hi:[1,0] neg_lo:[0,1] neg_hi:[0,1]
	v_pk_add_f32 v[232:233], v[232:233], v[246:247] op_sel_hi:[1,0] neg_lo:[0,1] neg_hi:[0,1]
	v_pk_add_f32 v[234:235], v[234:235], v[246:247] op_sel_hi:[1,0] neg_lo:[0,1] neg_hi:[0,1]
	v_pk_add_f32 v[236:237], v[236:237], v[246:247] op_sel_hi:[1,0] neg_lo:[0,1] neg_hi:[0,1]
	v_pk_add_f32 v[238:239], v[238:239], v[246:247] op_sel_hi:[1,0] neg_lo:[0,1] neg_hi:[0,1]
	v_pk_add_f32 v[240:241], v[240:241], v[246:247] op_sel_hi:[1,0] neg_lo:[0,1] neg_hi:[0,1]
	v_pk_add_f32 v[242:243], v[242:243], v[246:247] op_sel_hi:[1,0] neg_lo:[0,1] neg_hi:[0,1]
	v_exp_f32_e32 v162, v162
	v_exp_f32_e32 v163, v163
	v_exp_f32_e32 v164, v164
	v_exp_f32_e32 v165, v165
	v_exp_f32_e32 v166, v166
	v_exp_f32_e32 v167, v167
	v_exp_f32_e32 v168, v168
	v_exp_f32_e32 v169, v169
	v_exp_f32_e32 v170, v170
	v_exp_f32_e32 v171, v171
	v_exp_f32_e32 v172, v172
	v_exp_f32_e32 v173, v173
	v_exp_f32_e32 v174, v174
	v_exp_f32_e32 v175, v175
	v_exp_f32_e32 v176, v176
	v_exp_f32_e32 v177, v177
	v_exp_f32_e32 v228, v228
	v_exp_f32_e32 v229, v229
	v_exp_f32_e32 v230, v230
	v_exp_f32_e32 v231, v231
	v_exp_f32_e32 v232, v232
	v_exp_f32_e32 v233, v233
	v_exp_f32_e32 v234, v234
	v_exp_f32_e32 v235, v235
	v_exp_f32_e32 v236, v236
	v_exp_f32_e32 v237, v237
	v_exp_f32_e32 v238, v238
	v_exp_f32_e32 v239, v239
	v_exp_f32_e32 v240, v240
	v_exp_f32_e32 v241, v241
	v_exp_f32_e32 v242, v242
	v_exp_f32_e32 v243, v243
	v_pk_add_f32 v[250:251], v[162:163], v[164:165]
	v_pk_add_f32 v[250:251], v[250:251], v[166:167]
	v_pk_add_f32 v[250:251], v[250:251], v[168:169]
	v_pk_add_f32 v[250:251], v[250:251], v[170:171]
	v_pk_add_f32 v[250:251], v[250:251], v[172:173]
	v_pk_add_f32 v[250:251], v[250:251], v[174:175]
	v_pk_add_f32 v[250:251], v[250:251], v[176:177]
	v_pk_add_f32 v[250:251], v[250:251], v[228:229]
	v_pk_add_f32 v[250:251], v[250:251], v[230:231]
	v_pk_add_f32 v[250:251], v[250:251], v[232:233]
	v_pk_add_f32 v[250:251], v[250:251], v[234:235]
	v_pk_add_f32 v[250:251], v[250:251], v[236:237]
	v_pk_add_f32 v[250:251], v[250:251], v[238:239]
	v_pk_add_f32 v[250:251], v[250:251], v[240:241]
	v_pk_add_f32 v[250:251], v[250:251], v[242:243]
	s_nop 0
	v_add_f32_e32 v250, v250, v251
	v_cvt_pk_f16_f32 v144, v162, v163
	v_cvt_pk_f16_f32 v145, v164, v165
	v_cvt_pk_f16_f32 v146, v166, v167
	v_cvt_pk_f16_f32 v147, v168, v169
	v_cvt_pk_f16_f32 v148, v170, v171
	v_cvt_pk_f16_f32 v149, v172, v173
	v_cvt_pk_f16_f32 v150, v174, v175
	v_cvt_pk_f16_f32 v151, v176, v177
	v_cvt_pk_f16_f32 v152, v228, v229
	v_cvt_pk_f16_f32 v153, v230, v231
	v_cvt_pk_f16_f32 v154, v232, v233
	v_cvt_pk_f16_f32 v155, v234, v235
	v_cvt_pk_f16_f32 v178, v236, v237
	v_cvt_pk_f16_f32 v179, v238, v239
	v_cvt_pk_f16_f32 v180, v240, v241
	v_cvt_pk_f16_f32 v181, v242, v243
	s_cmp_lg_u32 s101, 0
	s_cbranch_scc1 .LdiffA_ok
	v_cmp_nge_f32_e32 vcc, 0x43800000, v250
	s_cbranch_vccz .LdiffA_ok
	s_mov_b32 s100, 0
	s_mov_b32 s101, 1
	s_branch .LdiffA_top

; __device__ __forceinline__ void diff_attn_item(CParams& p, int j, int layer, LAS unsigned char* lds, int b, int h, int qb, int tid_in, int lane_in, int wave) {
;     ...
;     const float inv = 1.f / l_run;
;     if (mp == 1) {
; #pragma unroll
;         for (int d = 0; d < 4; ++d)
; #pragma unroll
;             for (int i = 0; i < 16; ++i) Ox[(qs * 64 + d * 16 + i) * 64 + lane] = o[d][i] * inv;
;     }
;     __syncthreads();
.LdiffB_end:
.LBB0_744:
	s_or_b64 exec, exec, s[4:5]
	ds_bpermute_b32 v251, v185, v197
	s_waitcnt lgkmcnt(0)
	v_add_f32_e32 v197, v197, v251
	v_div_scale_f32 v66, s[4:5], v197, v197, 1.0
	v_rcp_f32_e32 v67, v66
	s_barrier
	v_fma_f32 v68, -v66, v67, 1.0
	v_fmac_f32_e32 v67, v68, v67
	v_div_scale_f32 v68, vcc, 1.0, v197, 1.0
	v_mul_f32_e32 v69, v68, v67
	v_fma_f32 v70, -v66, v69, v68
	v_fmac_f32_e32 v69, v70, v67
	v_fma_f32 v66, -v66, v69, v68
	v_div_fmas_f32 v66, v66, v67, v69
	v_div_fixup_f32 v68, v66, v197, 1.0
	s_and_saveexec_b64 s[4:5], s[8:9]
	s_cbranch_execz .LBB0_746
	v_mul_f32_e32 v66, v50, v68
	v_lshl_add_u32 v67, v193, 2, v188
	v_mul_f32_e32 v69, v51, v68
	ds_write2st64_b32 v67, v66, v69 offset1:1
	v_mul_f32_e32 v66, v52, v68
	v_mul_f32_e32 v69, v53, v68
	ds_write2st64_b32 v67, v66, v69 offset0:2 offset1:3
	v_mul_f32_e32 v66, v54, v68
	v_mul_f32_e32 v69, v55, v68
	ds_write2st64_b32 v67, v66, v69 offset0:4 offset1:5
	v_mul_f32_e32 v66, v56, v68
	v_mul_f32_e32 v69, v57, v68
	ds_write2st64_b32 v67, v66, v69 offset0:6 offset1:7
	v_mul_f32_e32 v66, v58, v68
	v_mul_f32_e32 v69, v59, v68
	ds_write2st64_b32 v67, v66, v69 offset0:8 offset1:9
	v_mul_f32_e32 v66, v60, v68
	v_mul_f32_e32 v69, v61, v68
	ds_write2st64_b32 v67, v66, v69 offset0:10 offset1:11
	v_mul_f32_e32 v66, v62, v68
	v_mul_f32_e32 v69, v63, v68
	ds_write2st64_b32 v67, v66, v69 offset0:12 offset1:13
	v_mul_f32_e32 v66, v64, v68
	v_mul_f32_e32 v69, v65, v68
	ds_write2st64_b32 v67, v66, v69 offset0:14 offset1:15
	v_mul_f32_e32 v66, v34, v68
	v_mul_f32_e32 v69, v35, v68
	ds_write2st64_b32 v67, v66, v69 offset0:16 offset1:17
	v_mul_f32_e32 v66, v36, v68
	v_mul_f32_e32 v69, v37, v68
	ds_write2st64_b32 v67, v66, v69 offset0:18 offset1:19
	v_mul_f32_e32 v66, v38, v68
	v_mul_f32_e32 v69, v39, v68
	ds_write2st64_b32 v67, v66, v69 offset0:20 offset1:21
	v_mul_f32_e32 v66, v40, v68
	v_mul_f32_e32 v69, v41, v68
	ds_write2st64_b32 v67, v66, v69 offset0:22 offset1:23
	v_mul_f32_e32 v66, v42, v68
	v_mul_f32_e32 v69, v43, v68
	ds_write2st64_b32 v67, v66, v69 offset0:24 offset1:25
	v_mul_f32_e32 v66, v44, v68
	v_mul_f32_e32 v69, v45, v68
	ds_write2st64_b32 v67, v66, v69 offset0:26 offset1:27
	v_mul_f32_e32 v66, v46, v68
	v_mul_f32_e32 v69, v47, v68
	ds_write2st64_b32 v67, v66, v69 offset0:28 offset1:29
	v_mul_f32_e32 v66, v48, v68
	v_mul_f32_e32 v69, v49, v68
	ds_write2st64_b32 v67, v66, v69 offset0:30 offset1:31
	v_mul_f32_e32 v66, v18, v68
	v_mul_f32_e32 v69, v19, v68
	ds_write2st64_b32 v67, v66, v69 offset0:32 offset1:33
	v_mul_f32_e32 v66, v20, v68
	v_mul_f32_e32 v69, v21, v68
	ds_write2st64_b32 v67, v66, v69 offset0:34 offset1:35
	v_mul_f32_e32 v66, v22, v68
	v_mul_f32_e32 v69, v23, v68
	ds_write2st64_b32 v67, v66, v69 offset0:36 offset1:37
	v_mul_f32_e32 v66, v24, v68
	v_mul_f32_e32 v69, v25, v68
	ds_write2st64_b32 v67, v66, v69 offset0:38 offset1:39
	v_mul_f32_e32 v66, v26, v68
	v_mul_f32_e32 v69, v27, v68
	ds_write2st64_b32 v67, v66, v69 offset0:40 offset1:41
	v_mul_f32_e32 v66, v28, v68
	v_mul_f32_e32 v69, v29, v68
	ds_write2st64_b32 v67, v66, v69 offset0:42 offset1:43
	v_mul_f32_e32 v66, v30, v68
	v_mul_f32_e32 v69, v31, v68
	ds_write2st64_b32 v67, v66, v69 offset0:44 offset1:45
	v_mul_f32_e32 v66, v32, v68
	v_mul_f32_e32 v69, v33, v68
	ds_write2st64_b32 v67, v66, v69 offset0:46 offset1:47
	v_mul_f32_e32 v66, v2, v68
	v_mul_f32_e32 v69, v3, v68
	ds_write2st64_b32 v67, v66, v69 offset0:48 offset1:49
	v_mul_f32_e32 v66, v4, v68
	v_mul_f32_e32 v69, v5, v68
	ds_write2st64_b32 v67, v66, v69 offset0:50 offset1:51
	v_mul_f32_e32 v66, v6, v68
	v_mul_f32_e32 v69, v7, v68
	ds_write2st64_b32 v67, v66, v69 offset0:52 offset1:53
	v_mul_f32_e32 v66, v8, v68
	v_mul_f32_e32 v69, v9, v68
	ds_write2st64_b32 v67, v66, v69 offset0:54 offset1:55
	v_mul_f32_e32 v66, v10, v68
	v_mul_f32_e32 v69, v11, v68
	ds_write2st64_b32 v67, v66, v69 offset0:56 offset1:57
	v_mul_f32_e32 v66, v12, v68
	v_mul_f32_e32 v69, v13, v68
	ds_write2st64_b32 v67, v66, v69 offset0:58 offset1:59
	v_mul_f32_e32 v66, v14, v68
	v_mul_f32_e32 v69, v15, v68
	ds_write2st64_b32 v67, v66, v69 offset0:60 offset1:61
	v_mul_f32_e32 v66, v16, v68
	v_mul_f32_e32 v69, v17, v68
	ds_write2st64_b32 v67, v66, v69 offset0:62 offset1:63
